# prep_x and final_norm scratch prefetch two rows ahead instead of one
# baseline (speedup 1.0000x reference)
.LBB0_226:
	v_lshl_add_u64 v[14:15], s[12:13], 0, v[4:5]
	v_add_co_u32_e64 v26, s[4:5], s0, v14
	s_waitcnt lgkmcnt(0)
	s_nop 1
	v_addc_co_u32_e64 v27, s[4:5], 0, v15, s[4:5]
	global_load_dwordx4 v[10:13], v[6:7], off offset:-2048
	global_load_dwordx4 v[14:17], v[6:7], off offset:-1024
	global_load_dwordx4 v[18:21], v[6:7], off
	global_load_dwordx4 v[22:25], v[6:7], off offset:1024
	s_lshl_b64 s[98:99], s[18:19], 1
	s_lshl_b32 s101, s10, 1
	s_add_i32 s101, s101, s8
	s_cmpk_lt_i32 s101, 0x4000
	s_cselect_b32 s98, s98, 0
	s_cselect_b32 s99, s99, 0
	v_lshl_add_u64 v[236:237], v[6:7], 0, s[98:99]
	global_load_dwordx4 v[238:241], v[236:237], off offset:-2048
	global_load_dwordx4 v[238:241], v[236:237], off offset:-1024
	global_load_dwordx4 v[238:241], v[236:237], off
	global_load_dwordx4 v[238:241], v[236:237], off offset:1024
	s_waitcnt vmcnt(7)
	v_cvt_pk_bf16_f32 v230, v10, v11
	v_cvt_pk_bf16_f32 v231, v12, v13
	global_store_dwordx2 v[26:27], v[230:231], off
	s_waitcnt vmcnt(7)
	v_cvt_pk_bf16_f32 v232, v14, v15
	v_cvt_pk_bf16_f32 v233, v16, v17
	global_store_dwordx2 v[26:27], v[232:233], off offset:512
	s_waitcnt vmcnt(7)
	v_cvt_pk_bf16_f32 v234, v18, v19
	v_cvt_pk_bf16_f32 v235, v20, v21
	global_store_dwordx2 v[26:27], v[234:235], off offset:1024
	v_mul_f32_e32 v11, v11, v11
	v_mul_f32_e32 v13, v13, v13
	v_fmac_f32_e32 v11, v10, v10
	v_fmac_f32_e32 v13, v12, v12
	v_add_f32_e32 v10, v11, v13
	v_mul_f32_e32 v11, v15, v15
	v_mul_f32_e32 v12, v17, v17
	v_fmac_f32_e32 v11, v14, v14
	v_fmac_f32_e32 v12, v16, v16
	v_add_f32_e32 v11, v11, v12
	v_add_f32_e32 v10, v10, v11
	v_mul_f32_e32 v11, v19, v19
	v_mul_f32_e32 v12, v21, v21
	v_fmac_f32_e32 v11, v18, v18
	v_fmac_f32_e32 v12, v20, v20
	v_add_f32_e32 v11, v11, v12
	v_add_f32_e32 v10, v10, v11
	s_waitcnt vmcnt(7)
	v_mul_f32_e32 v11, v23, v23
	v_mul_f32_e32 v12, v25, v25
	v_fmac_f32_e32 v11, v22, v22
	v_fmac_f32_e32 v12, v24, v24
	v_add_f32_e32 v11, v11, v12
	v_add_f32_e32 v10, v10, v11
	ds_bpermute_b32 v11, v8, v10
	v_cvt_pk_bf16_f32 v12, v22, v23
	v_cvt_pk_bf16_f32 v13, v24, v25
	global_store_dwordx2 v[26:27], v[12:13], off offset:1536
	s_waitcnt lgkmcnt(0)
	v_add_f32_e32 v10, v10, v11
	ds_bpermute_b32 v11, v9, v10
	s_and_saveexec_b64 s[4:5], vcc
	s_cbranch_execz .LBB0_225
	s_waitcnt lgkmcnt(0)
	v_add_f32_e32 v12, v10, v11
	v_lshl_add_u64 v[10:11], s[12:13], 0, v[2:3]
	global_store_dword v[10:11], v12, off
	s_branch .LBB0_225

.LBB0_3405:
	global_load_dwordx4 v[6:9], v1, s[2:3]
	global_load_dwordx4 v[10:13], v1, s[2:3] offset:16
	global_load_dwordx4 v[14:17], v1, s[2:3] offset:32
	global_load_dwordx4 v[18:21], v1, s[2:3] offset:48
	global_load_dwordx4 v[22:25], v[4:5], off offset:-2048
	global_load_dwordx4 v[30:33], v[4:5], off offset:-1024
	global_load_dwordx4 v[40:43], v[4:5], off
	global_load_dwordx4 v[44:47], v[4:5], off offset:1024
	s_add_i32 s11, s11, s0
	s_add_u32 s2, s2, s6
	s_addc_u32 s3, s3, s7
	s_lshl_b64 s[98:99], s[8:9], 1
	s_add_u32 s12, s2, s6
	s_addc_u32 s13, s3, s7
	s_add_i32 s101, s11, s0
	s_cmpk_lt_i32 s101, 0x4000
	s_cselect_b32 s98, s98, 0
	s_cselect_b32 s99, s99, 0
	s_cmpk_lt_i32 s11, 0x4000
	v_lshl_add_u64 v[236:237], v[4:5], 0, s[98:99]
	global_load_dwordx4 v[238:241], v1, s[12:13]
	global_load_dwordx4 v[238:241], v[236:237], off offset:-2048
	global_load_dwordx4 v[238:241], v[236:237], off offset:-1024
	global_load_dwordx4 v[238:241], v[236:237], off
	global_load_dwordx4 v[238:241], v[236:237], off offset:1024
	s_waitcnt vmcnt(12)
	v_mov_b32_e32 v34, v7
	v_mov_b32_e32 v35, v8
	v_mov_b32_e32 v7, v9
	s_waitcnt vmcnt(11)
	v_mov_b32_e32 v8, v11
	v_mov_b32_e32 v9, v12
	v_mov_b32_e32 v11, v13
	v_pk_add_f32 v[6:7], v[34:35], v[6:7]
	v_pk_add_f32 v[8:9], v[8:9], v[10:11]
	v_pk_add_f32 v[6:7], v[6:7], v[6:7] op_sel:[0,1] op_sel_hi:[1,0]
	v_pk_add_f32 v[8:9], v[8:9], v[8:9] op_sel:[0,1] op_sel_hi:[1,0]
	s_waitcnt vmcnt(10)
	v_add_f32_e32 v12, v14, v15
	v_add_f32_e32 v14, v16, v17
	s_waitcnt vmcnt(9)
	v_mov_b32_e32 v13, v20
	v_mov_b32_e32 v15, v21
	v_mov_b32_e32 v7, v18
	v_mov_b32_e32 v9, v19
	v_pk_add_f32 v[10:11], v[12:13], v[14:15]
	v_pk_add_f32 v[6:7], v[6:7], v[8:9]
	s_nop 0
	v_pk_add_f32 v[6:7], v[6:7], v[10:11]
	s_nop 0
	v_add_f32_e32 v6, v6, v7
	v_fmamk_f32 v6, v6, 0x3a800000, v0
	v_mul_f32_e32 v7, 0x4b800000, v6
	v_cmp_gt_f32_e32 vcc, s1, v6
	s_nop 1
	v_cndmask_b32_e32 v6, v6, v7, vcc
	v_rsq_f32_e32 v6, v6
	s_nop 0
	v_mul_f32_e32 v7, 0x45800000, v6
	v_cndmask_b32_e32 v18, v6, v7, vcc
	s_waitcnt vmcnt(8)
	v_pk_mul_f32 v[64:65], v[22:23], v[18:19] op_sel_hi:[1,0]
	v_pk_mul_f32 v[66:67], v[24:25], v[18:19] op_sel_hi:[1,0]
	v_pk_mul_f32 v[64:65], v[48:49], v[64:65]
	v_pk_mul_f32 v[66:67], v[50:51], v[66:67]
	global_store_dwordx4 v[4:5], v[64:67], off offset:-2048
	s_waitcnt vmcnt(8)
	v_pk_mul_f32 v[68:69], v[30:31], v[18:19] op_sel_hi:[1,0]
	v_pk_mul_f32 v[70:71], v[32:33], v[18:19] op_sel_hi:[1,0]
	v_pk_mul_f32 v[68:69], v[52:53], v[68:69]
	v_pk_mul_f32 v[70:71], v[54:55], v[70:71]
	global_store_dwordx4 v[4:5], v[68:71], off offset:-1024
	s_waitcnt vmcnt(8)
	v_pk_mul_f32 v[72:73], v[40:41], v[18:19] op_sel_hi:[1,0]
	v_pk_mul_f32 v[74:75], v[42:43], v[18:19] op_sel_hi:[1,0]
	v_pk_mul_f32 v[72:73], v[56:57], v[72:73]
	v_pk_mul_f32 v[74:75], v[58:59], v[74:75]
	global_store_dwordx4 v[4:5], v[72:75], off
	s_waitcnt vmcnt(8)
	v_pk_mul_f32 v[76:77], v[44:45], v[18:19] op_sel_hi:[1,0]
	v_pk_mul_f32 v[78:79], v[46:47], v[18:19] op_sel_hi:[1,0]
	v_pk_mul_f32 v[76:77], v[60:61], v[76:77]
	v_pk_mul_f32 v[78:79], v[62:63], v[78:79]
	global_store_dwordx4 v[4:5], v[76:79], off offset:1024
	v_lshl_add_u64 v[4:5], v[4:5], 0, s[8:9]
	s_cbranch_scc1 .LBB0_3405
